# v15: persistent running-max / -m*C registers with rare-path alpha (6 fewer VALU per tile), SALU rescale test, folded adds
# speedup vs baseline: 1.0138x; 1.0069x over previous
.LBB0_525:
	s_mul_i32 s7, s7, 0x9800
	s_mul_hi_u32 s8, s6, 0x9800
	s_and_b32 s4, s10, 15
	s_add_i32 s8, s8, s7
	s_mul_i32 s6, s6, 0x9800
	s_add_u32 s6, s50, s6
	s_addc_u32 s7, s51, s8
	s_lshl_b32 s4, s4, 8
	s_add_u32 s48, s6, s4
	s_addc_u32 s49, s7, 0
	s_lshl_b32 s4, s11, 2
	s_bfe_u32 s6, s10, 0x20002
	s_or_b32 s26, s4, s6
	v_mbcnt_lo_u32_b32 v76, -1, 0
	v_mbcnt_hi_u32_b32 v76, -1, v76
	s_mul_i32 s6, s26, 0x210000
	v_add_u32_e32 v54, s39, v76
	v_ashrrev_i32_e32 v16, 4, v54
	s_mul_hi_i32 s4, s26, 0x210000
	s_add_u32 s40, s52, s6
	v_lshlrev_b32_e32 v22, 3, v76
	v_add_u32_e32 v18, 32, v16
	s_addc_u32 s41, s53, s4
	v_and_b32_e32 v0, 0x78, v22
	v_ashrrev_i32_e32 v17, 31, v16
	v_ashrrev_i32_e32 v19, 31, v18
	s_add_u32 s42, s54, s6
	v_lshlrev_b32_e32 v23, 1, v0
	v_lshlrev_b64 v[48:49], 8, v[16:17]
	v_lshlrev_b64 v[8:9], 8, v[18:19]
	s_addc_u32 s43, s55, s4
	v_or_b32_e32 v52, v48, v23
	v_mov_b32_e32 v53, v49
	v_or_b32_e32 v8, v8, v23
	v_lshl_add_u64 v[0:1], s[42:43], 0, v[52:53]
	v_lshl_add_u64 v[4:5], s[42:43], 0, v[8:9]
	v_lshl_add_u64 v[10:11], s[40:41], 0, v[52:53]
	v_lshl_add_u64 v[12:13], s[40:41], 0, v[8:9]
	global_load_dwordx4 v[0:3], v[0:1], off
	s_nop 0
	global_load_dwordx4 v[4:7], v[4:5], off
	s_nop 0
	global_load_dwordx4 v[8:11], v[10:11], off
	s_nop 0
	global_load_dwordx4 v[12:15], v[12:13], off
	v_ashrrev_i32_e32 v55, 1, v54
	s_movk_i32 s4, 0xffe0
	v_bfe_u32 v97, v76, 5, 1
	v_bfi_b32 v17, s4, v55, v76
	v_mov_b64_e32 v[20:21], s[48:49]
	v_mad_i64_i32 v[20:21], s[6:7], v17, s21, v[20:21]
	v_lshlrev_b32_e32 v50, 4, v97
	v_mov_b32_e32 v51, v96
	v_lshl_add_u64 v[20:21], v[20:21], 0, v[50:51]
	global_load_dwordx4 v[118:121], v[20:21], off
	global_load_dwordx4 v[114:117], v[20:21], off offset:32
	global_load_dwordx4 v[126:129], v[20:21], off offset:64
	global_load_dwordx4 v[122:125], v[20:21], off offset:96
	global_load_dwordx4 v[110:113], v[20:21], off offset:128
	global_load_dwordx4 v[106:109], v[20:21], off offset:160
	global_load_dwordx4 v[102:105], v[20:21], off offset:192
	global_load_dwordx4 v[98:101], v[20:21], off offset:224
	v_bfe_u32 v17, v22, 5, 2
	v_and_b32_e32 v22, 0xfffff0, v16
	v_lshlrev_b32_e32 v24, 1, v16
	v_lshrrev_b32_e32 v25, 1, v16
	v_and_b32_e32 v26, 3, v16
	v_and_b32_e32 v19, 0xf0, v54
	v_lshlrev_b32_e32 v16, 8, v16
	v_and_or_b32 v22, v24, 8, v22
	v_bfe_u32 v24, v24, 1, 3
	v_and_b32_e32 v26, 0xfffff0, v18
	v_lshlrev_b32_e32 v27, 1, v18
	v_bitop3_b32 v16, v23, v16, v19 bitop3:0xde
	v_lshlrev_b32_e32 v18, 8, v18
	v_and_b32_e32 v22, 12, v25
	v_and_or_b32 v26, v27, 8, v26
	v_add_u32_e32 v188, 0, v16
	v_bitop3_b32 v16, v18, v23, v19 bitop3:0xf6
	v_or_b32_e32 v18, v22, v17
	v_and_or_b32 v19, v25, 12, 16
	v_and_b32_e32 v25, 48, v23
	v_lshlrev_b32_e32 v24, 6, v24
	v_add_u32_e32 v189, 0, v16
	v_lshlrev_b32_e32 v16, 9, v18
	v_or_b32_e32 v17, v19, v17
	v_or3_b32 v16, v16, v24, v25
	v_lshlrev_b32_e32 v17, 9, v17
	v_and_b32_e32 v180, 31, v76
	v_lshlrev_b32_e32 v51, 4, v76
	v_or3_b32 v17, v17, v24, v25
	v_add_u32_e32 v190, 0, v16
	v_add_u32_e32 v191, 0, v17
	s_waitcnt vmcnt(0)
	s_add_i32 s4, 0, 0x10000
	s_mov_b64 s[6:7], 0x6000
	v_and_b32_e32 v181, 0xffffffe0, v55
	v_and_b32_e32 v77, 63, v76
	s_mov_b32 s8, s5
	s_mov_b32 s9, s5
	s_mov_b32 s10, s5
	s_mov_b32 s11, s5
	s_mov_b32 s12, s5
	s_waitcnt vmcnt(0)
	ds_write_b128 v190, v[0:3]
	s_waitcnt vmcnt(10)
	ds_write_b128 v191, v[4:7]
	s_waitcnt vmcnt(9)
	ds_write_b128 v188, v[8:11] offset:32768
	s_waitcnt vmcnt(8)
	ds_write_b128 v189, v[12:15] offset:32768
	v_lshlrev_b32_e32 v12, 8, v180
	v_and_b32_e32 v13, 0xf0, v51
	v_bitop3_b32 v0, v50, v12, v13 bitop3:0xde
	v_add_u32_e32 v192, 0, v0
	s_waitcnt lgkmcnt(0)
	s_barrier
	ds_read_b128 v[0:3], v192 offset:32768
	ds_read_b128 v[4:7], v192 offset:40960
	s_waitcnt vmcnt(7) lgkmcnt(1)
	v_mfma_f32_32x32x16_bf16 v[16:31], v[0:3], v[118:121], 0
	v_or_b32_e32 v0, 32, v50
	v_bitop3_b32 v0, v0, v12, v13 bitop3:0xde
	v_add_u32_e32 v200, 0, v0
	v_lshl_add_u64 v[8:9], v[52:53], 0, s[6:7]
	v_lshl_add_u64 v[10:11], s[42:43], 0, v[8:9]
	v_lshlrev_b32_e32 v14, 3, v77
	v_and_b32_e32 v15, 0xc0, v51
	s_waitcnt lgkmcnt(0)
	v_mfma_f32_32x32x16_bf16 v[32:47], v[4:7], v[118:121], 0
	ds_read_b128 v[0:3], v200 offset:32768
	ds_read_b128 v[4:7], v200 offset:40960
	s_mov_b32 s6, s5
	s_mov_b32 s7, s5
	s_mov_b32 s13, s5
	s_mov_b32 s14, s5
	s_mov_b32 s15, s5
	s_mov_b32 s16, s5
	s_waitcnt vmcnt(6) lgkmcnt(1)
	v_mfma_f32_32x32x16_bf16 v[16:31], v[0:3], v[114:117], v[16:31]
	v_or_b32_e32 v0, 64, v50
	v_bitop3_b32 v0, v0, v12, v13 bitop3:0xde
	v_add_u32_e32 v199, 0, v0
	s_mov_b32 s17, s5
	s_mov_b32 s18, s5
	s_mov_b32 s19, s5
	s_cmp_lg_u32 0, -1
	s_waitcnt lgkmcnt(0)
	v_mfma_f32_32x32x16_bf16 v[32:47], v[4:7], v[114:117], v[32:47]
	ds_read_b128 v[0:3], v199 offset:32768
	ds_read_b128 v[4:7], v199 offset:40960
	s_cselect_b32 s27, 0, 0
	v_lshlrev_b32_e32 v183, 2, v97
	v_mov_b32_e32 v185, 0
	s_waitcnt vmcnt(5) lgkmcnt(1)
	v_mfma_f32_32x32x16_bf16 v[16:31], v[0:3], v[126:129], v[16:31]
	v_or_b32_e32 v0, 0x60, v50
	v_bitop3_b32 v0, v0, v12, v13 bitop3:0xde
	v_add_u32_e32 v198, 0, v0
	s_waitcnt lgkmcnt(0)
	v_mfma_f32_32x32x16_bf16 v[32:47], v[4:7], v[126:129], v[32:47]
	ds_read_b128 v[0:3], v198 offset:32768
	ds_read_b128 v[4:7], v198 offset:40960
	s_waitcnt vmcnt(4) lgkmcnt(1)
	v_mfma_f32_32x32x16_bf16 v[16:31], v[0:3], v[122:125], v[16:31]
	v_or_b32_e32 v0, 0x80, v50
	v_bitop3_b32 v0, v0, v12, v13 bitop3:0xde
	v_add_u32_e32 v195, 0, v0
	s_waitcnt lgkmcnt(0)
	v_mfma_f32_32x32x16_bf16 v[32:47], v[4:7], v[122:125], v[32:47]
	ds_read_b128 v[0:3], v195 offset:32768
	ds_read_b128 v[4:7], v195 offset:40960
	s_waitcnt vmcnt(3) lgkmcnt(1)
	v_mfma_f32_32x32x16_bf16 v[16:31], v[0:3], v[110:113], v[16:31]
	v_or_b32_e32 v0, 0xa0, v50
	v_bitop3_b32 v0, v0, v12, v13 bitop3:0xde
	v_add_u32_e32 v193, 0, v0
	ds_read_b128 v[0:3], v193 offset:32768
	s_waitcnt lgkmcnt(1)
	v_mfma_f32_32x32x16_bf16 v[32:47], v[4:7], v[110:113], v[32:47]
	v_and_b32_e32 v4, 0x3fffffc0, v54
	v_lshl_add_u32 v78, v4, 2, s4
	ds_read_b128 v[4:7], v193 offset:40960
	s_mov_b32 s4, s5
	v_add_u32_e32 v182, v78, v50
	v_lshl_add_u32 v184, v180, 2, v78
	s_waitcnt vmcnt(2) lgkmcnt(1)
	v_mfma_f32_32x32x16_bf16 v[16:31], v[0:3], v[106:109], v[16:31]
	v_lshl_add_u64 v[0:1], v[52:53], 0, s[68:69]
	v_lshl_add_u64 v[2:3], s[42:43], 0, v[0:1]
	v_lshl_add_u64 v[0:1], s[40:41], 0, v[0:1]
	global_load_dwordx4 v[54:57], v[2:3], off
	global_load_dwordx4 v[58:61], v[10:11], off
	v_lshl_add_u64 v[2:3], s[40:41], 0, v[8:9]
	global_load_dwordx4 v[62:65], v[0:1], off
	global_load_dwordx4 v[66:69], v[2:3], off
	v_or_b32_e32 v0, 0xc0, v50
	v_bitop3_b32 v0, v0, v12, v13 bitop3:0xde
	v_add_u32_e32 v202, 0, v0
	ds_read_b128 v[0:3], v202 offset:32768
	v_lshlrev_b32_e32 v9, 1, v76
	v_and_or_b32 v8, v14, 24, v15
	s_waitcnt lgkmcnt(1)
	v_mfma_f32_32x32x16_bf16 v[32:47], v[4:7], v[106:109], v[32:47]
	v_and_b32_e32 v4, 32, v9
	v_and_b32_e32 v5, 0x100, v14
	v_or3_b32 v51, v8, v4, v5
	ds_read_b128 v[4:7], v202 offset:40960
	v_add_u32_e32 v187, s27, v51
	s_waitcnt vmcnt(5) lgkmcnt(1)
	v_mfma_f32_32x32x16_bf16 v[16:31], v[0:3], v[102:105], v[16:31]
	v_or_b32_e32 v0, 0xe0, v50
	v_bitop3_b32 v0, v0, v12, v13 bitop3:0xde
	v_add_u32_e32 v201, 0, v0
	ds_read_b128 v[0:3], v201 offset:32768
	ds_read_b128 v[70:73], v201 offset:40960
	s_waitcnt lgkmcnt(2)
	v_mfma_f32_32x32x16_bf16 v[32:47], v[4:7], v[102:105], v[32:47]
	s_waitcnt vmcnt(4) lgkmcnt(1)
	v_mfma_f32_32x32x16_bf16 v[16:31], v[0:3], v[98:101], v[16:31]
	v_mov_b64_e32 v[0:1], s[4:5]
	v_mov_b64_e32 v[2:3], s[6:7]
	v_mov_b64_e32 v[4:5], s[8:9]
	v_mov_b64_e32 v[6:7], s[10:11]
	v_mov_b64_e32 v[8:9], s[12:13]
	v_mov_b64_e32 v[10:11], s[14:15]
	v_mov_b64_e32 v[12:13], s[16:17]
	s_waitcnt lgkmcnt(0)
	v_mfma_f32_32x32x16_bf16 v[32:47], v[70:73], v[98:101], v[32:47]
	s_nop 2
	v_max_f32_e32 v70, v17, v17
	v_max_f32_e32 v71, v16, v16
	v_max_f32_e32 v70, v71, v70
	v_max3_f32 v70, v70, v18, v19
	v_max3_f32 v70, v70, v20, v21
	v_max3_f32 v70, v70, v22, v23
	v_max3_f32 v70, v70, v24, v25
	v_max3_f32 v70, v70, v26, v27
	v_max3_f32 v70, v70, v28, v29
	v_max3_f32 v70, v70, v30, v31
	v_max3_f32 v70, v70, v32, v33
	v_max3_f32 v70, v70, v34, v35
	v_max3_f32 v70, v70, v36, v37
	v_max3_f32 v70, v70, v38, v39
	v_max3_f32 v70, v70, v40, v41
	v_max3_f32 v70, v70, v42, v43
	v_mov_b64_e32 v[14:15], s[18:19]
	v_max3_f32 v70, v70, v44, v45
	s_mov_b64 s[6:7], 0x8000
	v_max3_f32 v79, v70, v46, v47
	v_lshl_add_u64 v[70:71], v[52:53], 0, s[6:7]
	s_mov_b64 s[6:7], 0xa000
	v_lshl_add_u64 v[72:73], s[42:43], 0, v[70:71]
	v_lshl_add_u64 v[52:53], v[52:53], 0, s[6:7]
	v_lshl_add_u64 v[70:71], s[40:41], 0, v[70:71]
	v_lshl_add_u64 v[74:75], s[42:43], 0, v[52:53]
	global_load_dwordx4 v[130:133], v[72:73], off
	global_load_dwordx4 v[138:141], v[74:75], off
	v_lshl_add_u64 v[52:53], s[40:41], 0, v[52:53]
	global_load_dwordx4 v[134:137], v[70:71], off
	global_load_dwordx4 v[142:145], v[52:53], off
	v_mov_b32_e32 v80, v79
	s_nop 1
	v_permlane32_swap_b32_e32 v79, v80
	v_max_f32_e32 v52, v80, v80
	v_max_f32_e32 v53, v79, v79
	v_max_f32_e32 v52, v53, v52
	v_add_f32_e32 v53, 0x7149f2ca, v52
	v_max_f32_e32 v52, 0xf149f2ca, v52
	v_cmp_ge_f32_e32 vcc, s92, v53
	v_sub_f32_e32 v53, 0xf149f2ca, v52
	v_mul_f32_e32 v53, 0x3e0293ee, v53
	v_exp_f32_e32 v53, v53
	s_cmp_eq_u64 vcc, exec
	s_cselect_b64 vcc, -1, 0
	s_waitcnt vmcnt(4)
	v_cndmask_b32_e64 v203, v53, 1.0, vcc
	v_mov_b32_e32 v53, 0xf149f2ca
	v_cndmask_b32_e32 v170, v52, v53, vcc
	v_mul_f32_e32 v52, 0xbe0293ee, v170
	v_fmamk_f32 v16, v16, 0x3e0293ee, v52
	v_exp_f32_e32 v163, v16
	v_fmamk_f32 v16, v17, 0x3e0293ee, v52
	v_exp_f32_e32 v177, v16
	v_fmamk_f32 v16, v18, 0x3e0293ee, v52
	v_exp_f32_e32 v164, v16
	v_fmamk_f32 v16, v19, 0x3e0293ee, v52
	v_exp_f32_e32 v207, v16
	v_fmamk_f32 v16, v20, 0x3e0293ee, v52
	v_exp_f32_e32 v176, v16
	v_fmamk_f32 v16, v21, 0x3e0293ee, v52
	v_exp_f32_e32 v210, v16
	v_fmamk_f32 v16, v22, 0x3e0293ee, v52
	v_exp_f32_e32 v165, v16
	v_fmamk_f32 v16, v23, 0x3e0293ee, v52
	v_exp_f32_e32 v175, v16
	v_fmamk_f32 v16, v24, 0x3e0293ee, v52
	v_exp_f32_e32 v166, v16
	v_fmamk_f32 v16, v25, 0x3e0293ee, v52
	v_exp_f32_e32 v173, v16
	v_fmamk_f32 v16, v26, 0x3e0293ee, v52
	v_exp_f32_e32 v167, v16
	v_fmamk_f32 v16, v27, 0x3e0293ee, v52
	v_exp_f32_e32 v174, v16
	v_fmamk_f32 v16, v28, 0x3e0293ee, v52
	v_exp_f32_e32 v168, v16
	v_fmamk_f32 v16, v29, 0x3e0293ee, v52
	v_exp_f32_e32 v171, v16
	v_fmamk_f32 v16, v30, 0x3e0293ee, v52
	v_pk_fma_f32 v[146:147], v[46:47], s[88:89], v[52:53] op_sel_hi:[1,0,0]
	v_pk_fma_f32 v[152:153], v[44:45], s[88:89], v[52:53] op_sel_hi:[1,0,0]
	v_pk_fma_f32 v[156:157], v[42:43], s[88:89], v[52:53] op_sel_hi:[1,0,0]
	v_pk_fma_f32 v[148:149], v[40:41], s[88:89], v[52:53] op_sel_hi:[1,0,0]
	v_pk_fma_f32 v[150:151], v[38:39], s[88:89], v[52:53] op_sel_hi:[1,0,0]
	v_pk_fma_f32 v[154:155], v[36:37], s[88:89], v[52:53] op_sel_hi:[1,0,0]
	v_pk_fma_f32 v[158:159], v[34:35], s[88:89], v[52:53] op_sel_hi:[1,0,0]
	v_pk_fma_f32 v[160:161], v[32:33], s[88:89], v[52:53] op_sel_hi:[1,0,0]
	v_exp_f32_e32 v169, v16
	v_fmac_f32_e32 v52, 0x3e0293ee, v31
	v_mov_b32_e32 v16, 0x210000
	v_exp_f32_e32 v172, v52
	v_mad_i64_i32 v[16:17], s[6:7], s26, v16, v[48:49]
	v_and_b32_e32 v18, 15, v76
	s_addk_i32 s27, 0x4000
	v_lshl_or_b32 v16, v18, 4, v16
	s_waitcnt vmcnt(7)
	ds_write_b128 v190, v[54:57] offset:16384
	s_waitcnt vmcnt(6)
	ds_write_b128 v191, v[58:61] offset:16384
	s_waitcnt vmcnt(5)
	ds_write_b128 v188, v[62:65] offset:49152
	s_waitcnt vmcnt(4)
	ds_write_b128 v189, v[66:69] offset:49152
	v_add_u32_e32 v186, s27, v51
	v_lshl_add_u64 v[178:179], s[46:47], 0, v[16:17]
	v_mov_b64_e32 v[62:63], v[14:15]
	v_mov_b64_e32 v[46:47], v[14:15]
	v_mov_b64_e32 v[30:31], v[14:15]
	v_cmp_gt_u32_e64 s[40:41], 32, v77
	v_mov_b64_e32 v[60:61], v[12:13]
	v_mov_b64_e32 v[58:59], v[10:11]
	v_mov_b64_e32 v[56:57], v[8:9]
	v_mov_b64_e32 v[54:55], v[6:7]
	v_mov_b64_e32 v[52:53], v[4:5]
	v_mov_b64_e32 v[50:51], v[2:3]
	v_mov_b64_e32 v[48:49], v[0:1]
	v_mov_b64_e32 v[44:45], v[12:13]
	v_mov_b64_e32 v[42:43], v[10:11]
	v_mov_b64_e32 v[40:41], v[8:9]
	v_mov_b64_e32 v[38:39], v[6:7]
	v_mov_b64_e32 v[36:37], v[4:5]
	v_mov_b64_e32 v[34:35], v[2:3]
	v_mov_b64_e32 v[32:33], v[0:1]
	v_mov_b64_e32 v[28:29], v[12:13]
	v_mov_b64_e32 v[26:27], v[10:11]
	v_mov_b64_e32 v[24:25], v[8:9]
	v_mov_b64_e32 v[22:23], v[6:7]
	v_mov_b64_e32 v[20:21], v[4:5]
	v_mov_b64_e32 v[18:19], v[2:3]
	v_mov_b64_e32 v[16:17], v[0:1]
	s_waitcnt lgkmcnt(0)
	s_barrier
	v_readfirstlane_b32 s66, v178
	v_readfirstlane_b32 s67, v179
	s_nop 3
	v_subrev_u32_e32 v178, s66, v178
	v_add_u32_e32 v179, 0x2000, v178
	s_add_u32 s98, s66, 0xfef7a000
	s_addc_u32 s99, s67, -1
	s_add_u32 s66, s66, 0xffffa000
	s_addc_u32 s67, s67, -1
	v_mov_b32_e32 v243, v170
	v_mul_f32_e32 v242, 0xbe0293ee, v243
.LBB0_526:
	ds_read_b128 v[64:67], v192 offset:49152
	ds_read_b128 v[68:71], v192 offset:57344
	ds_read_b128 v[232:235], v200 offset:49152
	ds_read_b128 v[236:239], v200 offset:57344
	ds_read_b128 v[250:253], v199 offset:49152
	ds_read_b128 v[244:247], v199 offset:57344
	ds_read_b128 v[212:215], v198 offset:49152
	ds_read_b128 v[216:219], v198 offset:57344
	v_add_f32_e32 v162, v163, v177
	s_waitcnt lgkmcnt(6)
	v_mfma_f32_32x32x16_bf16 v[80:95], v[64:67], v[118:121], 0
	v_add_f32_e32 v162, v164, v162
	v_add_f32_e32 v162, v207, v162
	v_add_f32_e32 v162, v176, v162
	v_add_f32_e32 v162, v210, v162
	v_mfma_f32_32x32x16_bf16 v[64:79], v[68:71], v[118:121], 0
	v_add_f32_e32 v162, v165, v162
	v_add_f32_e32 v162, v175, v162
	v_add_f32_e32 v162, v166, v162
	v_add_f32_e32 v162, v173, v162
	v_add_f32_e32 v162, v167, v162
	s_waitcnt lgkmcnt(4)
	v_mfma_f32_32x32x16_bf16 v[80:95], v[232:235], v[114:117], v[80:95]
	ds_read_b128 v[232:235], v195 offset:49152
	v_add_f32_e32 v162, v174, v162
	v_exp_f32_e32 v160, v160
	v_add_f32_e32 v162, v168, v162
	v_exp_f32_e32 v161, v161
	v_mfma_f32_32x32x16_bf16 v[64:79], v[236:239], v[114:117], v[64:79]
	ds_read_b128 v[236:239], v195 offset:57344
	v_add_f32_e32 v162, v171, v162
	v_exp_f32_e32 v158, v158
	v_add_f32_e32 v162, v169, v162
	v_exp_f32_e32 v159, v159
	s_waitcnt lgkmcnt(4)
	v_mfma_f32_32x32x16_bf16 v[80:95], v[250:253], v[126:129], v[80:95]
	ds_read_b128 v[250:253], v193 offset:49152
	v_add_f32_e32 v162, v172, v162
	v_exp_f32_e32 v154, v154
	v_add_f32_e32 v162, v160, v162
	v_exp_f32_e32 v155, v155
	v_mfma_f32_32x32x16_bf16 v[64:79], v[244:247], v[126:129], v[64:79]
	ds_read_b128 v[244:247], v193 offset:57344
	v_add_f32_e32 v162, v161, v162
	v_exp_f32_e32 v150, v150
	v_add_f32_e32 v162, v158, v162
	v_exp_f32_e32 v151, v151
	s_waitcnt lgkmcnt(4)
	v_mfma_f32_32x32x16_bf16 v[80:95], v[212:215], v[122:125], v[80:95]
	ds_read_b128 v[212:215], v202 offset:49152
	v_add_f32_e32 v162, v159, v162
	v_exp_f32_e32 v148, v148
	v_add_f32_e32 v162, v154, v162
	v_exp_f32_e32 v149, v149
	v_mfma_f32_32x32x16_bf16 v[64:79], v[216:219], v[122:125], v[64:79]
	ds_read_b128 v[216:219], v202 offset:57344
	v_add_f32_e32 v162, v155, v162
	v_exp_f32_e32 v156, v156
	v_add_f32_e32 v162, v150, v162
	v_exp_f32_e32 v157, v157
	s_waitcnt lgkmcnt(4)
	v_mfma_f32_32x32x16_bf16 v[80:95], v[232:235], v[110:113], v[80:95]
	ds_read_b128 v[232:235], v201 offset:49152
	v_add_f32_e32 v162, v151, v162
	v_exp_f32_e32 v152, v152
	v_add_f32_e32 v162, v148, v162
	v_exp_f32_e32 v153, v153
	v_mfma_f32_32x32x16_bf16 v[64:79], v[236:239], v[110:113], v[64:79]
	ds_read_b128 v[236:239], v201 offset:57344
	v_add_f32_e32 v162, v149, v162
	v_exp_f32_e32 v146, v146
	v_add_f32_e32 v162, v156, v162
	v_exp_f32_e32 v147, v147
	s_waitcnt lgkmcnt(4)
	v_mfma_f32_32x32x16_bf16 v[80:95], v[250:253], v[106:109], v[80:95]
	v_add_f32_e32 v162, v157, v162
	v_add_f32_e32 v162, v152, v162
	v_add_f32_e32 v162, v153, v162
	v_add_f32_e32 v162, v146, v162
	v_add_f32_e32 v204, v147, v162
	v_mov_b32_e32 v205, v204
	v_mfma_f32_32x32x16_bf16 v[64:79], v[244:247], v[106:109], v[64:79]
	s_nop 0
	v_permlane32_swap_b32_e32 v204, v205
	v_cvt_pk_bf16_f32 v162, v163, v177
	v_cvt_pk_bf16_f32 v163, v164, v207
	v_cvt_pk_bf16_f32 v164, v176, v210
	s_waitcnt lgkmcnt(2)
	v_mfma_f32_32x32x16_bf16 v[80:95], v[212:215], v[102:105], v[80:95]
	v_cvt_pk_bf16_f32 v165, v165, v175
	v_cvt_pk_bf16_f32 v166, v166, v173
	v_cvt_pk_bf16_f32 v167, v167, v174
	v_cvt_pk_bf16_f32 v168, v168, v171
	v_mfma_f32_32x32x16_bf16 v[64:79], v[216:219], v[102:105], v[64:79]
	v_cvt_pk_bf16_f32 v169, v169, v172
	v_cvt_pk_bf16_f32 v172, v160, v161
	v_cvt_pk_bf16_f32 v173, v158, v159
	v_cvt_pk_bf16_f32 v174, v154, v155
	ds_read_b64_tr_b16 v[210:211], v187 offset:0x0
	ds_read_b64_tr_b16 v[212:213], v187 offset:0x800
	ds_read_b64_tr_b16 v[214:215], v187 offset:0x200
	ds_read_b64_tr_b16 v[216:217], v187 offset:0xa00
	ds_read_b64_tr_b16 v[218:219], v187 offset:0x400
	ds_read_b64_tr_b16 v[220:221], v187 offset:0xc00
	ds_read_b64_tr_b16 v[222:223], v187 offset:0x600
	ds_read_b64_tr_b16 v[224:225], v187 offset:0xe00
	s_waitcnt lgkmcnt(8)
	v_mfma_f32_32x32x16_bf16 v[80:95], v[232:235], v[98:101], v[80:95]
	v_cvt_pk_bf16_f32 v175, v150, v151
	v_cvt_pk_bf16_f32 v206, v148, v149
	v_cvt_pk_bf16_f32 v207, v156, v157
	v_mfma_f32_32x32x16_bf16 v[64:79], v[236:239], v[98:101], v[64:79]
	v_cvt_pk_bf16_f32 v208, v152, v153
	v_cvt_pk_bf16_f32 v209, v146, v147
	s_waitcnt vmcnt(0)
	ds_write_b128 v188, v[134:137] offset:32768
	ds_write_b128 v189, v[142:145] offset:32768
	global_load_dwordx4 v[146:149], v178, s[66:67]
	global_load_dwordx4 v[150:153], v179, s[66:67]
	global_load_dwordx4 v[154:157], v178, s[98:99]
	global_load_dwordx4 v[158:161], v179, s[98:99]
	s_add_u32 s66, s66, 0x4000
	s_addc_u32 s67, s67, 0
	s_add_u32 s98, s98, 0x4000
	s_addc_u32 s99, s99, 0
	s_waitcnt lgkmcnt(6)
	v_mfma_f32_32x32x16_bf16 v[0:15], v[162:165], v[210:213], v[0:15]
	ds_read_b64_tr_b16 v[210:211], v187 offset:0x1000
	ds_read_b64_tr_b16 v[212:213], v187 offset:0x1800
	v_max_f32_e32 v240, v80, v81
	v_max3_f32 v240, v240, v82, v83
	v_max3_f32 v240, v240, v84, v85
	v_max3_f32 v240, v240, v86, v87
	v_max3_f32 v240, v240, v88, v89
	v_mfma_f32_32x32x16_bf16 v[48:63], v[162:165], v[214:217], v[48:63]
	ds_read_b64_tr_b16 v[214:215], v187 offset:0x1200
	ds_read_b64_tr_b16 v[216:217], v187 offset:0x1a00
	v_max3_f32 v240, v240, v90, v91
	v_max3_f32 v240, v240, v92, v93
	v_max3_f32 v240, v240, v94, v95
	v_max3_f32 v240, v240, v64, v65
	v_max3_f32 v240, v240, v66, v67
	v_max3_f32 v240, v240, v68, v69
	s_waitcnt lgkmcnt(6)
	v_mfma_f32_32x32x16_bf16 v[32:47], v[162:165], v[218:221], v[32:47]
	ds_read_b64_tr_b16 v[218:219], v187 offset:0x1400
	ds_read_b64_tr_b16 v[220:221], v187 offset:0x1c00
	v_max3_f32 v240, v240, v70, v71
	v_max3_f32 v240, v240, v72, v73
	v_max3_f32 v240, v240, v74, v75
	v_max3_f32 v240, v240, v76, v77
	v_max3_f32 v240, v240, v78, v79
	v_mfma_f32_32x32x16_bf16 v[16:31], v[162:165], v[222:225], v[16:31]
	ds_read_b64_tr_b16 v[222:223], v187 offset:0x1600
	ds_read_b64_tr_b16 v[224:225], v187 offset:0x1e00
	v_mov_b32_e32 v241, v240
	s_nop 1
	v_permlane32_swap_b32_e32 v240, v241
	v_max_f32_e32 v240, v240, v241
	v_sub_f32_e32 v241, v240, v243
	v_cmp_ge_f32_e32 vcc, s92, v241
	s_waitcnt lgkmcnt(4)
	v_mfma_f32_32x32x16_bf16 v[0:15], v[166:169], v[210:213], v[0:15]
	ds_read_b64_tr_b16 v[210:211], v187 offset:0x2000
	ds_read_b64_tr_b16 v[212:213], v187 offset:0x2800
	s_cmp_eq_u64 vcc, exec
	s_cselect_b64 s[42:43], -1, 0
	s_cbranch_scc1 .Lattn_common_a
	v_max_f32_e32 v240, v243, v240
	v_sub_f32_e32 v241, v243, v240
	v_mul_f32_e32 v241, 0x3e0293ee, v241
	v_exp_f32_e32 v241, v241
	v_mov_b32_e32 v243, v240
	v_mul_f32_e32 v242, 0xbe0293ee, v243
.Lattn_common_a:
	v_mfma_f32_32x32x16_bf16 v[48:63], v[166:169], v[214:217], v[48:63]
	ds_read_b64_tr_b16 v[214:215], v187 offset:0x2200
	ds_read_b64_tr_b16 v[216:217], v187 offset:0x2a00
	v_fmamk_f32 v80, v80, 0x3e0293ee, v242
	v_fmamk_f32 v81, v81, 0x3e0293ee, v242
	v_fmamk_f32 v82, v82, 0x3e0293ee, v242
	v_fmamk_f32 v83, v83, 0x3e0293ee, v242
	s_waitcnt lgkmcnt(4)
	v_mfma_f32_32x32x16_bf16 v[32:47], v[166:169], v[218:221], v[32:47]
	ds_read_b64_tr_b16 v[218:219], v187 offset:0x2400
	ds_read_b64_tr_b16 v[220:221], v187 offset:0x2c00
	v_fmamk_f32 v84, v84, 0x3e0293ee, v242
	v_fmamk_f32 v85, v85, 0x3e0293ee, v242
	v_fmamk_f32 v86, v86, 0x3e0293ee, v242
	v_fmamk_f32 v87, v87, 0x3e0293ee, v242
	v_fmamk_f32 v88, v88, 0x3e0293ee, v242
	v_fmamk_f32 v89, v89, 0x3e0293ee, v242
	v_mfma_f32_32x32x16_bf16 v[16:31], v[166:169], v[222:225], v[16:31]
	ds_read_b64_tr_b16 v[222:223], v187 offset:0x2600
	ds_read_b64_tr_b16 v[224:225], v187 offset:0x2e00
	v_fmamk_f32 v90, v90, 0x3e0293ee, v242
	v_fmamk_f32 v91, v91, 0x3e0293ee, v242
	v_fmamk_f32 v92, v92, 0x3e0293ee, v242
	v_fmamk_f32 v93, v93, 0x3e0293ee, v242
	v_fmamk_f32 v94, v94, 0x3e0293ee, v242
	v_fmamk_f32 v95, v95, 0x3e0293ee, v242
	s_waitcnt lgkmcnt(4)
	v_mfma_f32_32x32x16_bf16 v[0:15], v[172:175], v[210:213], v[0:15]
	ds_read_b64_tr_b16 v[210:211], v187 offset:0x3000
	ds_read_b64_tr_b16 v[212:213], v187 offset:0x3800
	v_exp_f32_e32 v177, v81
	v_exp_f32_e32 v176, v83
	v_exp_f32_e32 v171, v93
	v_mfma_f32_32x32x16_bf16 v[48:63], v[172:175], v[214:217], v[48:63]
	ds_read_b64_tr_b16 v[214:215], v187 offset:0x3200
	ds_read_b64_tr_b16 v[216:217], v187 offset:0x3a00
	v_exp_f32_e32 v170, v95
	v_exp_f32_e32 v162, v80
	v_exp_f32_e32 v163, v82
	s_waitcnt lgkmcnt(4)
	v_mfma_f32_32x32x16_bf16 v[32:47], v[172:175], v[218:221], v[32:47]
	ds_read_b64_tr_b16 v[218:219], v187 offset:0x3400
	ds_read_b64_tr_b16 v[220:221], v187 offset:0x3c00
	v_exp_f32_e32 v164, v84
	v_exp_f32_e32 v165, v86
	v_exp_f32_e32 v166, v88
	v_mfma_f32_32x32x16_bf16 v[16:31], v[172:175], v[222:225], v[16:31]
	ds_read_b64_tr_b16 v[222:223], v187 offset:0x3600
	ds_read_b64_tr_b16 v[224:225], v187 offset:0x3e00
	v_exp_f32_e32 v167, v90
	v_exp_f32_e32 v168, v92
	v_exp_f32_e32 v169, v94
	s_waitcnt lgkmcnt(4)
	v_mfma_f32_32x32x16_bf16 v[0:15], v[206:209], v[210:213], v[0:15]
	v_exp_f32_e32 v175, v85
	v_exp_f32_e32 v174, v87
	v_exp_f32_e32 v173, v89
	v_mfma_f32_32x32x16_bf16 v[48:63], v[206:209], v[214:217], v[48:63]
	v_exp_f32_e32 v172, v91
	s_waitcnt lgkmcnt(0)
	v_mfma_f32_32x32x16_bf16 v[32:47], v[206:209], v[218:221], v[32:47]
	v_mfma_f32_32x32x16_bf16 v[16:31], v[206:209], v[222:225], v[16:31]
	s_barrier
	v_cndmask_b32_e64 v206, v241, 1.0, s[42:43]
	ds_write_b128 v190, v[130:133]
	ds_write_b128 v191, v[138:141]
	s_cmp_lg_u64 s[42:43], 0
	s_cbranch_scc1 .LBB0_530
	s_and_saveexec_b64 s[6:7], s[40:41]
	ds_write_b32 v184, v206 offset:128
	s_or_b64 exec, exec, s[6:7]
	s_waitcnt lgkmcnt(0)
	ds_read_b128 v[210:213], v182 offset:224
	ds_read_b128 v[214:217], v182 offset:192
	ds_read_b128 v[218:221], v182 offset:160
	ds_read_b128 v[222:225], v182 offset:128
	s_waitcnt lgkmcnt(3)
	v_pk_mul_f32 v[14:15], v[14:15], v[212:213]
	s_waitcnt lgkmcnt(2)
	v_pk_mul_f32 v[10:11], v[10:11], v[216:217]
	s_waitcnt lgkmcnt(1)
	v_pk_mul_f32 v[6:7], v[6:7], v[220:221]
	s_waitcnt lgkmcnt(0)
	v_pk_mul_f32 v[2:3], v[2:3], v[224:225]
	v_pk_mul_f32 v[12:13], v[12:13], v[210:211]
	v_pk_mul_f32 v[8:9], v[8:9], v[214:215]
	v_pk_mul_f32 v[4:5], v[4:5], v[218:219]
	v_pk_mul_f32 v[0:1], v[0:1], v[222:223]
	v_pk_mul_f32 v[62:63], v[62:63], v[212:213]
	v_pk_mul_f32 v[58:59], v[58:59], v[216:217]
	v_pk_mul_f32 v[54:55], v[54:55], v[220:221]
	v_pk_mul_f32 v[50:51], v[50:51], v[224:225]
	v_pk_mul_f32 v[60:61], v[60:61], v[210:211]
	v_pk_mul_f32 v[56:57], v[56:57], v[214:215]
	v_pk_mul_f32 v[52:53], v[52:53], v[218:219]
	v_pk_mul_f32 v[48:49], v[48:49], v[222:223]
	v_pk_mul_f32 v[46:47], v[46:47], v[212:213]
	v_pk_mul_f32 v[42:43], v[42:43], v[216:217]
	v_pk_mul_f32 v[38:39], v[38:39], v[220:221]
	v_pk_mul_f32 v[34:35], v[34:35], v[224:225]
	v_pk_mul_f32 v[44:45], v[44:45], v[210:211]
	v_pk_mul_f32 v[40:41], v[40:41], v[214:215]
	v_pk_mul_f32 v[36:37], v[36:37], v[218:219]
	v_pk_mul_f32 v[32:33], v[32:33], v[222:223]
	v_pk_mul_f32 v[30:31], v[30:31], v[212:213]
	v_pk_mul_f32 v[26:27], v[26:27], v[216:217]
	v_pk_mul_f32 v[22:23], v[22:23], v[220:221]
	v_pk_mul_f32 v[18:19], v[18:19], v[224:225]
	v_pk_mul_f32 v[28:29], v[28:29], v[210:211]
	v_pk_mul_f32 v[24:25], v[24:25], v[214:215]
	v_pk_mul_f32 v[20:21], v[20:21], v[218:219]
	v_pk_mul_f32 v[16:17], v[16:17], v[222:223]
.LBB0_530:
	v_fmamk_f32 v217, v64, 0x3e0293ee, v242
	v_fmamk_f32 v218, v65, 0x3e0293ee, v242
	v_fmamk_f32 v219, v66, 0x3e0293ee, v242
	v_fmamk_f32 v220, v67, 0x3e0293ee, v242
	v_fmamk_f32 v221, v68, 0x3e0293ee, v242
	v_fmamk_f32 v210, v69, 0x3e0293ee, v242
	v_fmamk_f32 v211, v70, 0x3e0293ee, v242
	v_fmamk_f32 v212, v71, 0x3e0293ee, v242
	v_fmamk_f32 v213, v72, 0x3e0293ee, v242
	v_fmamk_f32 v214, v73, 0x3e0293ee, v242
	v_fmamk_f32 v215, v74, 0x3e0293ee, v242
	v_fmamk_f32 v216, v75, 0x3e0293ee, v242
	v_fmamk_f32 v209, v76, 0x3e0293ee, v242
	v_fmamk_f32 v222, v77, 0x3e0293ee, v242
	v_fmamk_f32 v223, v78, 0x3e0293ee, v242
	v_fmamk_f32 v208, v79, 0x3e0293ee, v242
	s_waitcnt lgkmcnt(0)
	s_barrier
	ds_read_b128 v[64:67], v192 offset:32768
	ds_read_b128 v[68:71], v192 offset:40960
	ds_read_b128 v[232:235], v200 offset:32768
	ds_read_b128 v[236:239], v200 offset:40960
	ds_read_b128 v[250:253], v199 offset:32768
	ds_read_b128 v[244:247], v199 offset:40960
	ds_read_b128 v[224:227], v198 offset:32768
	ds_read_b128 v[228:231], v198 offset:40960
	v_exp_f32_e32 v248, v208
	v_exp_f32_e32 v249, v209
	s_waitcnt lgkmcnt(6)
	v_mfma_f32_32x32x16_bf16 v[80:95], v[64:67], v[118:121], 0
	v_exp_f32_e32 v217, v217
	v_add_f32_e32 v208, v162, v177
	v_exp_f32_e32 v218, v218
	v_mfma_f32_32x32x16_bf16 v[64:79], v[68:71], v[118:121], 0
	v_add_f32_e32 v208, v163, v208
	v_exp_f32_e32 v219, v219
	v_add_f32_e32 v208, v176, v208
	v_exp_f32_e32 v220, v220
	v_add_f32_e32 v208, v164, v208
	s_waitcnt lgkmcnt(4)
	v_mfma_f32_32x32x16_bf16 v[80:95], v[232:235], v[114:117], v[80:95]
	ds_read_b128 v[232:235], v195 offset:32768
	v_exp_f32_e32 v221, v221
	v_add_f32_e32 v208, v175, v208
	v_exp_f32_e32 v210, v210
	v_add_f32_e32 v208, v165, v208
	v_mfma_f32_32x32x16_bf16 v[64:79], v[236:239], v[114:117], v[64:79]
	ds_read_b128 v[236:239], v195 offset:40960
	v_exp_f32_e32 v211, v211
	v_add_f32_e32 v208, v174, v208
	v_exp_f32_e32 v212, v212
	v_add_f32_e32 v208, v166, v208
	s_waitcnt lgkmcnt(4)
	v_mfma_f32_32x32x16_bf16 v[80:95], v[250:253], v[126:129], v[80:95]
	ds_read_b128 v[250:253], v193 offset:32768
	v_exp_f32_e32 v213, v213
	v_add_f32_e32 v208, v173, v208
	v_exp_f32_e32 v214, v214
	v_add_f32_e32 v208, v167, v208
	v_mfma_f32_32x32x16_bf16 v[64:79], v[244:247], v[126:129], v[64:79]
	ds_read_b128 v[244:247], v193 offset:40960
	v_exp_f32_e32 v215, v215
	v_add_f32_e32 v208, v172, v208
	v_exp_f32_e32 v216, v216
	v_add_f32_e32 v208, v168, v208
	s_waitcnt lgkmcnt(4)
	v_mfma_f32_32x32x16_bf16 v[80:95], v[224:227], v[122:125], v[80:95]
	ds_read_b128 v[224:227], v202 offset:32768
	v_exp_f32_e32 v222, v222
	v_add_f32_e32 v208, v171, v208
	v_exp_f32_e32 v223, v223
	v_add_f32_e32 v208, v169, v208
	v_mfma_f32_32x32x16_bf16 v[64:79], v[228:231], v[122:125], v[64:79]
	ds_read_b128 v[228:231], v202 offset:40960
	v_add_f32_e32 v208, v170, v208
	v_add_f32_e32 v208, v217, v208
	v_add_f32_e32 v208, v218, v208
	v_add_f32_e32 v208, v219, v208
	s_waitcnt lgkmcnt(4)
	v_mfma_f32_32x32x16_bf16 v[80:95], v[232:235], v[110:113], v[80:95]
	ds_read_b128 v[232:235], v201 offset:32768
	v_add_f32_e32 v208, v220, v208
	v_add_f32_e32 v208, v221, v208
	v_add_f32_e32 v208, v210, v208
	v_add_f32_e32 v208, v211, v208
	v_mfma_f32_32x32x16_bf16 v[64:79], v[236:239], v[110:113], v[64:79]
	ds_read_b128 v[236:239], v201 offset:40960
	v_add_f32_e32 v208, v212, v208
	v_add_f32_e32 v208, v213, v208
	v_add_f32_e32 v208, v214, v208
	v_add_f32_e32 v208, v215, v208
	s_waitcnt lgkmcnt(4)
	v_mfma_f32_32x32x16_bf16 v[80:95], v[250:253], v[106:109], v[80:95]
	v_add_f32_e32 v208, v216, v208
	v_add_f32_e32 v208, v249, v208
	v_add_f32_e32 v208, v222, v208
	v_add_f32_e32 v208, v223, v208
	v_mfma_f32_32x32x16_bf16 v[64:79], v[244:247], v[106:109], v[64:79]
	v_add_f32_e32 v208, v248, v208
	v_mov_b32_e32 v209, v208
	v_cvt_pk_bf16_f32 v162, v162, v177
	v_cvt_pk_bf16_f32 v163, v163, v176
	s_waitcnt lgkmcnt(2)
	v_mfma_f32_32x32x16_bf16 v[80:95], v[224:227], v[102:105], v[80:95]
	v_cvt_pk_bf16_f32 v164, v164, v175
	v_cvt_pk_bf16_f32 v165, v165, v174
	v_cvt_pk_bf16_f32 v166, v166, v173
	v_cvt_pk_bf16_f32 v167, v167, v172
	v_mfma_f32_32x32x16_bf16 v[64:79], v[228:231], v[102:105], v[64:79]
	v_cvt_pk_bf16_f32 v168, v168, v171
	v_cvt_pk_bf16_f32 v169, v169, v170
	v_cvt_pk_bf16_f32 v170, v217, v218
	v_cvt_pk_bf16_f32 v171, v219, v220
	s_waitcnt lgkmcnt(0)
	v_mfma_f32_32x32x16_bf16 v[80:95], v[232:235], v[98:101], v[80:95]
	v_cvt_pk_bf16_f32 v172, v221, v210
	v_cvt_pk_bf16_f32 v173, v211, v212
	v_cvt_pk_bf16_f32 v174, v213, v214
	v_cvt_pk_bf16_f32 v175, v215, v216
	v_mfma_f32_32x32x16_bf16 v[64:79], v[236:239], v[98:101], v[64:79]
	v_cvt_pk_bf16_f32 v176, v249, v222
	v_cvt_pk_bf16_f32 v177, v223, v248
	ds_read_b64_tr_b16 v[210:211], v186 offset:0x0
	ds_read_b64_tr_b16 v[212:213], v186 offset:0x800
	ds_read_b64_tr_b16 v[214:215], v186 offset:0x200
	ds_read_b64_tr_b16 v[216:217], v186 offset:0xa00
	ds_read_b64_tr_b16 v[218:219], v186 offset:0x400
	ds_read_b64_tr_b16 v[220:221], v186 offset:0xc00
	ds_read_b64_tr_b16 v[222:223], v186 offset:0x600
	ds_read_b64_tr_b16 v[224:225], v186 offset:0xe00
	s_nop 1
	v_permlane32_swap_b32_e32 v208, v209
	s_waitcnt vmcnt(1)
	ds_write_b128 v188, v[154:157] offset:49152
	s_waitcnt vmcnt(0)
	ds_write_b128 v189, v[158:161] offset:49152
	s_cmp_ge_u32 s34, s35
	s_cselect_b64 s[6:7], -1, 0
	s_cbranch_scc1 .LBB0_532
	global_load_dwordx4 v[130:133], v178, s[66:67]
	global_load_dwordx4 v[134:137], v178, s[98:99]
	global_load_dwordx4 v[138:141], v179, s[66:67]
	global_load_dwordx4 v[142:145], v179, s[98:99]
	s_add_u32 s66, s66, 0x4000
	s_addc_u32 s67, s67, 0
	s_add_u32 s98, s98, 0x4000
	s_addc_u32 s99, s99, 0
.LBB0_532:
	s_waitcnt lgkmcnt(6)
	v_mfma_f32_32x32x16_bf16 v[0:15], v[162:165], v[210:213], v[0:15]
	ds_read_b64_tr_b16 v[210:211], v186 offset:0x1000
	ds_read_b64_tr_b16 v[212:213], v186 offset:0x1800
	v_max_f32_e32 v240, v80, v81
	v_max3_f32 v240, v240, v82, v83
	v_max3_f32 v240, v240, v84, v85
	v_max3_f32 v240, v240, v86, v87
	v_max3_f32 v240, v240, v88, v89
	v_mfma_f32_32x32x16_bf16 v[48:63], v[162:165], v[214:217], v[48:63]
	ds_read_b64_tr_b16 v[214:215], v186 offset:0x1200
	ds_read_b64_tr_b16 v[216:217], v186 offset:0x1a00
	v_max3_f32 v240, v240, v90, v91
	v_max3_f32 v240, v240, v92, v93
	v_max3_f32 v240, v240, v94, v95
	v_max3_f32 v240, v240, v64, v65
	v_max3_f32 v240, v240, v66, v67
	v_max3_f32 v240, v240, v68, v69
	s_waitcnt lgkmcnt(6)
	v_mfma_f32_32x32x16_bf16 v[32:47], v[162:165], v[218:221], v[32:47]
	ds_read_b64_tr_b16 v[218:219], v186 offset:0x1400
	ds_read_b64_tr_b16 v[220:221], v186 offset:0x1c00
	v_max3_f32 v240, v240, v70, v71
	v_max3_f32 v240, v240, v72, v73
	v_max3_f32 v240, v240, v74, v75
	v_max3_f32 v240, v240, v76, v77
	v_max3_f32 v240, v240, v78, v79
	v_mfma_f32_32x32x16_bf16 v[16:31], v[162:165], v[222:225], v[16:31]
	ds_read_b64_tr_b16 v[222:223], v186 offset:0x1600
	ds_read_b64_tr_b16 v[224:225], v186 offset:0x1e00
	v_mov_b32_e32 v241, v240
	s_nop 1
	v_permlane32_swap_b32_e32 v240, v241
	v_max_f32_e32 v240, v240, v241
	v_sub_f32_e32 v241, v240, v243
	v_cmp_ge_f32_e32 vcc, s92, v241
	s_waitcnt lgkmcnt(4)
	v_mfma_f32_32x32x16_bf16 v[0:15], v[166:169], v[210:213], v[0:15]
	ds_read_b64_tr_b16 v[210:211], v186 offset:0x2000
	ds_read_b64_tr_b16 v[212:213], v186 offset:0x2800
	s_cmp_eq_u64 vcc, exec
	s_cselect_b64 s[42:43], -1, 0
	s_cbranch_scc1 .Lattn_common_b
	v_max_f32_e32 v240, v243, v240
	v_sub_f32_e32 v241, v243, v240
	v_mul_f32_e32 v241, 0x3e0293ee, v241
	v_exp_f32_e32 v241, v241
	v_mov_b32_e32 v243, v240
	v_mul_f32_e32 v242, 0xbe0293ee, v243
.Lattn_common_b:
	v_mfma_f32_32x32x16_bf16 v[48:63], v[166:169], v[214:217], v[48:63]
	ds_read_b64_tr_b16 v[214:215], v186 offset:0x2200
	ds_read_b64_tr_b16 v[216:217], v186 offset:0x2a00
	v_fmamk_f32 v80, v80, 0x3e0293ee, v242
	v_fmamk_f32 v81, v81, 0x3e0293ee, v242
	v_fmamk_f32 v82, v82, 0x3e0293ee, v242
	v_fmamk_f32 v83, v83, 0x3e0293ee, v242
	s_waitcnt lgkmcnt(4)
	v_mfma_f32_32x32x16_bf16 v[32:47], v[166:169], v[218:221], v[32:47]
	ds_read_b64_tr_b16 v[218:219], v186 offset:0x2400
	ds_read_b64_tr_b16 v[220:221], v186 offset:0x2c00
	v_fmamk_f32 v84, v84, 0x3e0293ee, v242
	v_fmamk_f32 v85, v85, 0x3e0293ee, v242
	v_fmamk_f32 v86, v86, 0x3e0293ee, v242
	v_fmamk_f32 v87, v87, 0x3e0293ee, v242
	v_fmamk_f32 v88, v88, 0x3e0293ee, v242
	v_fmamk_f32 v89, v89, 0x3e0293ee, v242
	v_mfma_f32_32x32x16_bf16 v[16:31], v[166:169], v[222:225], v[16:31]
	ds_read_b64_tr_b16 v[222:223], v186 offset:0x2600
	ds_read_b64_tr_b16 v[224:225], v186 offset:0x2e00
	v_fmamk_f32 v90, v90, 0x3e0293ee, v242
	v_fmamk_f32 v91, v91, 0x3e0293ee, v242
	v_fmamk_f32 v92, v92, 0x3e0293ee, v242
	v_fmamk_f32 v93, v93, 0x3e0293ee, v242
	v_fmamk_f32 v94, v94, 0x3e0293ee, v242
	v_fmamk_f32 v95, v95, 0x3e0293ee, v242
	s_waitcnt lgkmcnt(4)
	v_mfma_f32_32x32x16_bf16 v[0:15], v[170:173], v[210:213], v[0:15]
	ds_read_b64_tr_b16 v[210:211], v186 offset:0x3000
	ds_read_b64_tr_b16 v[212:213], v186 offset:0x3800
	v_exp_f32_e32 v207, v83
	v_exp_f32_e32 v163, v80
	v_exp_f32_e32 v164, v82
	v_mfma_f32_32x32x16_bf16 v[48:63], v[170:173], v[214:217], v[48:63]
	ds_read_b64_tr_b16 v[214:215], v186 offset:0x3200
	ds_read_b64_tr_b16 v[216:217], v186 offset:0x3a00
	v_exp_f32_e32 v165, v86
	v_exp_f32_e32 v166, v88
	v_exp_f32_e32 v167, v90
	s_waitcnt lgkmcnt(4)
	v_mfma_f32_32x32x16_bf16 v[32:47], v[170:173], v[218:221], v[32:47]
	ds_read_b64_tr_b16 v[218:219], v186 offset:0x3400
	ds_read_b64_tr_b16 v[220:221], v186 offset:0x3c00
	v_exp_f32_e32 v168, v92
	v_exp_f32_e32 v169, v94
	v_mfma_f32_32x32x16_bf16 v[16:31], v[170:173], v[222:225], v[16:31]
	ds_read_b64_tr_b16 v[222:223], v186 offset:0x3600
	ds_read_b64_tr_b16 v[224:225], v186 offset:0x3e00
	s_waitcnt lgkmcnt(4)
	v_mfma_f32_32x32x16_bf16 v[0:15], v[174:177], v[210:213], v[0:15]
	v_exp_f32_e32 v171, v93
	v_exp_f32_e32 v172, v95
	v_exp_f32_e32 v173, v89
	v_mfma_f32_32x32x16_bf16 v[48:63], v[174:177], v[214:217], v[48:63]
	v_exp_f32_e32 v210, v85
	s_waitcnt lgkmcnt(0)
	v_mfma_f32_32x32x16_bf16 v[32:47], v[174:177], v[218:221], v[32:47]
	v_mfma_f32_32x32x16_bf16 v[16:31], v[174:177], v[222:225], v[16:31]
	v_exp_f32_e32 v174, v91
	v_exp_f32_e32 v175, v87
	v_exp_f32_e32 v176, v84
	v_exp_f32_e32 v177, v81
	s_barrier
	v_cndmask_b32_e64 v162, v241, 1.0, s[42:43]
	ds_write_b128 v190, v[146:149] offset:16384
	ds_write_b128 v191, v[150:153] offset:16384
	s_cmp_lg_u64 s[42:43], 0
	s_cbranch_scc1 .LBB0_536
	s_and_saveexec_b64 s[8:9], s[40:41]
	ds_write_b32 v184, v162 offset:128
	s_or_b64 exec, exec, s[8:9]
	s_waitcnt lgkmcnt(0)
	ds_read_b128 v[146:149], v182 offset:224
	ds_read_b128 v[150:153], v182 offset:192
	ds_read_b128 v[154:157], v182 offset:160
	ds_read_b128 v[158:161], v182 offset:128
	s_waitcnt lgkmcnt(3)
	v_pk_mul_f32 v[14:15], v[14:15], v[148:149]
	s_waitcnt lgkmcnt(2)
	v_pk_mul_f32 v[10:11], v[10:11], v[152:153]
	s_waitcnt lgkmcnt(1)
	v_pk_mul_f32 v[6:7], v[6:7], v[156:157]
	s_waitcnt lgkmcnt(0)
	v_pk_mul_f32 v[2:3], v[2:3], v[160:161]
	v_pk_mul_f32 v[12:13], v[12:13], v[146:147]
	v_pk_mul_f32 v[8:9], v[8:9], v[150:151]
	v_pk_mul_f32 v[4:5], v[4:5], v[154:155]
	v_pk_mul_f32 v[0:1], v[0:1], v[158:159]
	v_pk_mul_f32 v[62:63], v[62:63], v[148:149]
	v_pk_mul_f32 v[58:59], v[58:59], v[152:153]
	v_pk_mul_f32 v[54:55], v[54:55], v[156:157]
	v_pk_mul_f32 v[50:51], v[50:51], v[160:161]
	v_pk_mul_f32 v[60:61], v[60:61], v[146:147]
	v_pk_mul_f32 v[56:57], v[56:57], v[150:151]
	v_pk_mul_f32 v[52:53], v[52:53], v[154:155]
	v_pk_mul_f32 v[48:49], v[48:49], v[158:159]
	v_pk_mul_f32 v[46:47], v[46:47], v[148:149]
	v_pk_mul_f32 v[42:43], v[42:43], v[152:153]
	v_pk_mul_f32 v[38:39], v[38:39], v[156:157]
	v_pk_mul_f32 v[34:35], v[34:35], v[160:161]
	v_pk_mul_f32 v[44:45], v[44:45], v[146:147]
	v_pk_mul_f32 v[40:41], v[40:41], v[150:151]
	v_pk_mul_f32 v[36:37], v[36:37], v[154:155]
	v_pk_mul_f32 v[32:33], v[32:33], v[158:159]
	v_pk_mul_f32 v[30:31], v[30:31], v[148:149]
	v_pk_mul_f32 v[26:27], v[26:27], v[152:153]
	v_pk_mul_f32 v[22:23], v[22:23], v[156:157]
	v_pk_mul_f32 v[18:19], v[18:19], v[160:161]
	v_pk_mul_f32 v[28:29], v[28:29], v[146:147]
	v_pk_mul_f32 v[24:25], v[24:25], v[150:151]
	v_pk_mul_f32 v[20:21], v[20:21], v[154:155]
	v_pk_mul_f32 v[16:17], v[16:17], v[158:159]
.LBB0_536:
	v_pk_fma_f32 v[160:161], v[64:65], s[88:89], v[242:243] op_sel_hi:[1,0,0]
	v_add_f32_e32 v64, v204, v205
	v_fmac_f32_e32 v64, v203, v185
	v_add_f32_e32 v185, v208, v209
	v_pk_fma_f32 v[158:159], v[66:67], s[88:89], v[242:243] op_sel_hi:[1,0,0]
	v_pk_fma_f32 v[154:155], v[68:69], s[88:89], v[242:243] op_sel_hi:[1,0,0]
	v_pk_fma_f32 v[150:151], v[70:71], s[88:89], v[242:243] op_sel_hi:[1,0,0]
	v_pk_fma_f32 v[148:149], v[72:73], s[88:89], v[242:243] op_sel_hi:[1,0,0]
	v_pk_fma_f32 v[156:157], v[74:75], s[88:89], v[242:243] op_sel_hi:[1,0,0]
	v_pk_fma_f32 v[152:153], v[76:77], s[88:89], v[242:243] op_sel_hi:[1,0,0]
	v_pk_fma_f32 v[146:147], v[78:79], s[88:89], v[242:243] op_sel_hi:[1,0,0]
	v_fmac_f32_e32 v185, v64, v206
	s_add_i32 s34, s34, 2
	s_and_b64 vcc, exec, s[6:7]
	s_waitcnt lgkmcnt(0)
	s_barrier
	s_cbranch_vccnz .LBB0_538
	v_mov_b32_e32 v203, v162
	s_branch .LBB0_526
.LBB0_538:
	v_mov_b32_e32 v170, v243
	ds_read_b128 v[64:67], v192 offset:49152
	ds_read_b128 v[68:71], v192 offset:57344
	s_waitcnt lgkmcnt(1)
	v_mfma_f32_32x32x16_bf16 v[80:95], v[64:67], v[118:121], 0
	s_waitcnt lgkmcnt(0)
	v_mfma_f32_32x32x16_bf16 v[64:79], v[68:71], v[118:121], 0
	ds_read_b128 v[118:121], v200 offset:49152
	ds_read_b128 v[130:133], v200 offset:57344
	s_waitcnt lgkmcnt(1)
	v_mfma_f32_32x32x16_bf16 v[80:95], v[118:121], v[114:117], v[80:95]
	s_waitcnt lgkmcnt(0)
	v_mfma_f32_32x32x16_bf16 v[64:79], v[130:133], v[114:117], v[64:79]
	ds_read_b128 v[114:117], v199 offset:49152
	ds_read_b128 v[118:121], v199 offset:57344
	s_waitcnt lgkmcnt(1)
	v_mfma_f32_32x32x16_bf16 v[80:95], v[114:117], v[126:129], v[80:95]
	s_waitcnt lgkmcnt(0)
	v_mfma_f32_32x32x16_bf16 v[64:79], v[118:121], v[126:129], v[64:79]
	ds_read_b128 v[114:117], v198 offset:49152
	ds_read_b128 v[118:121], v198 offset:57344
	s_waitcnt lgkmcnt(1)
	v_mfma_f32_32x32x16_bf16 v[80:95], v[114:117], v[122:125], v[80:95]
	s_waitcnt lgkmcnt(0)
	v_mfma_f32_32x32x16_bf16 v[64:79], v[118:121], v[122:125], v[64:79]
	ds_read_b128 v[114:117], v195 offset:49152
	ds_read_b128 v[118:121], v195 offset:57344
	v_exp_f32_e32 v122, v146
	v_exp_f32_e32 v123, v147
	s_waitcnt lgkmcnt(1)
	v_mfma_f32_32x32x16_bf16 v[80:95], v[114:117], v[110:113], v[80:95]
	s_waitcnt lgkmcnt(0)
	v_mfma_f32_32x32x16_bf16 v[64:79], v[118:121], v[110:113], v[64:79]
	ds_read_b128 v[110:113], v193 offset:49152
	ds_read_b128 v[114:117], v193 offset:57344
	v_exp_f32_e32 v118, v156
	v_exp_f32_e32 v119, v157
	v_exp_f32_e32 v120, v152
	v_exp_f32_e32 v121, v153
	s_waitcnt lgkmcnt(1)
	v_mfma_f32_32x32x16_bf16 v[80:95], v[110:113], v[106:109], v[80:95]
	s_waitcnt lgkmcnt(0)
	v_mfma_f32_32x32x16_bf16 v[64:79], v[114:117], v[106:109], v[64:79]
	ds_read_b128 v[106:109], v202 offset:49152
	ds_read_b128 v[110:113], v202 offset:57344
	v_exp_f32_e32 v114, v150
	v_exp_f32_e32 v115, v151
	v_exp_f32_e32 v116, v148
	v_exp_f32_e32 v117, v149
	s_waitcnt lgkmcnt(1)
	v_mfma_f32_32x32x16_bf16 v[80:95], v[106:109], v[102:105], v[80:95]
	s_waitcnt lgkmcnt(0)
	v_mfma_f32_32x32x16_bf16 v[64:79], v[110:113], v[102:105], v[64:79]
	ds_read_b128 v[102:105], v201 offset:49152
	ds_read_b128 v[106:109], v201 offset:57344
	v_exp_f32_e32 v110, v158
	v_exp_f32_e32 v111, v159
	v_exp_f32_e32 v112, v154
	v_exp_f32_e32 v113, v155
	s_waitcnt lgkmcnt(1)
	v_mfma_f32_32x32x16_bf16 v[80:95], v[102:105], v[98:101], v[80:95]
	s_waitcnt lgkmcnt(0)
	v_mfma_f32_32x32x16_bf16 v[64:79], v[106:109], v[98:101], v[64:79]
	v_add_f32_e32 v98, 0, v163
	v_add_f32_e32 v98, v177, v98
	v_add_f32_e32 v98, v164, v98
	v_add_f32_e32 v98, v207, v98
	v_add_f32_e32 v98, v176, v98
	v_add_f32_e32 v98, v210, v98
	v_add_f32_e32 v98, v165, v98
	v_add_f32_e32 v98, v175, v98
	v_add_f32_e32 v98, v166, v98
	v_add_f32_e32 v98, v173, v98
	v_add_f32_e32 v98, v167, v98
	v_add_f32_e32 v98, v174, v98
	v_exp_f32_e32 v108, v160
	v_add_f32_e32 v98, v168, v98
	v_exp_f32_e32 v109, v161
	v_add_f32_e32 v98, v171, v98
	v_add_f32_e32 v98, v169, v98
	v_add_f32_e32 v98, v172, v98
	v_add_f32_e32 v98, v108, v98
	v_add_f32_e32 v98, v109, v98
	v_add_f32_e32 v98, v110, v98
	v_add_f32_e32 v98, v111, v98
	v_add_f32_e32 v98, v112, v98
	v_add_f32_e32 v98, v113, v98
	v_add_f32_e32 v98, v114, v98
	v_add_f32_e32 v98, v115, v98
	v_add_f32_e32 v98, v116, v98
	v_add_f32_e32 v98, v117, v98
	v_add_f32_e32 v98, v118, v98
	v_add_f32_e32 v98, v119, v98
	v_add_f32_e32 v98, v120, v98
	v_add_f32_e32 v98, v121, v98
	v_add_f32_e32 v98, v122, v98
	v_add_f32_e32 v98, v123, v98
	v_mov_b32_e32 v99, v98
	v_cvt_pk_bf16_f32 v100, v163, v177
	v_cvt_pk_bf16_f32 v101, v164, v207
	v_cvt_pk_bf16_f32 v102, v176, v210
	v_cvt_pk_bf16_f32 v103, v165, v175
	s_nop 1
	v_permlane32_swap_b32_e32 v98, v99
	v_cvt_pk_bf16_f32 v104, v166, v173
	v_cvt_pk_bf16_f32 v105, v167, v174
	v_cvt_pk_bf16_f32 v106, v168, v171
	v_cvt_pk_bf16_f32 v107, v169, v172
	v_cvt_pk_bf16_f32 v108, v108, v109
	v_cvt_pk_bf16_f32 v109, v110, v111
	v_cvt_pk_bf16_f32 v110, v112, v113
	v_cvt_pk_bf16_f32 v111, v114, v115
	v_cvt_pk_bf16_f32 v112, v116, v117
	v_cvt_pk_bf16_f32 v113, v118, v119
	v_cvt_pk_bf16_f32 v114, v120, v121
	v_cvt_pk_bf16_f32 v115, v122, v123
	s_nop 0
	ds_read_b64_tr_b16 v[116:117], v187 offset:0
	ds_read_b64_tr_b16 v[118:119], v187 offset:0x800
	ds_read_b64_tr_b16 v[120:121], v187 offset:0x1000
	ds_read_b64_tr_b16 v[122:123], v187 offset:0x1800
	ds_read_b64_tr_b16 v[124:125], v187 offset:0x2000
	ds_read_b64_tr_b16 v[126:127], v187 offset:0x2800
	ds_read_b64_tr_b16 v[128:129], v187 offset:0x3000
	ds_read_b64_tr_b16 v[130:131], v187 offset:0x3800
	s_waitcnt lgkmcnt(0)
	s_nop 0
	v_mfma_f32_32x32x16_bf16 v[0:15], v[100:103], v[116:119], v[0:15]
	ds_read_b64_tr_b16 v[116:117], v187 offset:0x200
	ds_read_b64_tr_b16 v[118:119], v187 offset:0xa00
	v_mfma_f32_32x32x16_bf16 v[0:15], v[104:107], v[120:123], v[0:15]
	ds_read_b64_tr_b16 v[120:121], v187 offset:0x1200
	ds_read_b64_tr_b16 v[122:123], v187 offset:0x1a00
	v_mfma_f32_32x32x16_bf16 v[0:15], v[108:111], v[124:127], v[0:15]
	ds_read_b64_tr_b16 v[124:125], v187 offset:0x2200
	ds_read_b64_tr_b16 v[126:127], v187 offset:0x2a00
	v_mfma_f32_32x32x16_bf16 v[0:15], v[112:115], v[128:131], v[0:15]
	ds_read_b64_tr_b16 v[128:129], v187 offset:0x3200
	ds_read_b64_tr_b16 v[130:131], v187 offset:0x3a00
	s_waitcnt lgkmcnt(0)
	v_mfma_f32_32x32x16_bf16 v[48:63], v[100:103], v[116:119], v[48:63]
	ds_read_b64_tr_b16 v[116:117], v187 offset:0x400
	ds_read_b64_tr_b16 v[118:119], v187 offset:0xc00
	v_mfma_f32_32x32x16_bf16 v[48:63], v[104:107], v[120:123], v[48:63]
	ds_read_b64_tr_b16 v[120:121], v187 offset:0x1400
	ds_read_b64_tr_b16 v[122:123], v187 offset:0x1c00
	v_mfma_f32_32x32x16_bf16 v[48:63], v[108:111], v[124:127], v[48:63]
	ds_read_b64_tr_b16 v[124:125], v187 offset:0x2400
	ds_read_b64_tr_b16 v[126:127], v187 offset:0x2c00
	v_mfma_f32_32x32x16_bf16 v[48:63], v[112:115], v[128:131], v[48:63]
	ds_read_b64_tr_b16 v[128:129], v187 offset:0x3400
	ds_read_b64_tr_b16 v[130:131], v187 offset:0x3c00
	s_waitcnt lgkmcnt(0)
	v_mfma_f32_32x32x16_bf16 v[32:47], v[100:103], v[116:119], v[32:47]
	ds_read_b64_tr_b16 v[116:117], v187 offset:0x600
	ds_read_b64_tr_b16 v[118:119], v187 offset:0xe00
	v_mfma_f32_32x32x16_bf16 v[32:47], v[104:107], v[120:123], v[32:47]
	ds_read_b64_tr_b16 v[120:121], v187 offset:0x1600
	ds_read_b64_tr_b16 v[122:123], v187 offset:0x1e00
	v_mfma_f32_32x32x16_bf16 v[32:47], v[108:111], v[124:127], v[32:47]
	ds_read_b64_tr_b16 v[124:125], v187 offset:0x2600
	ds_read_b64_tr_b16 v[126:127], v187 offset:0x2e00
	v_mfma_f32_32x32x16_bf16 v[32:47], v[112:115], v[128:131], v[32:47]
	ds_read_b64_tr_b16 v[128:129], v187 offset:0x3600
	ds_read_b64_tr_b16 v[130:131], v187 offset:0x3e00
	s_waitcnt lgkmcnt(0)
	v_mfma_f32_32x32x16_bf16 v[16:31], v[100:103], v[116:119], v[16:31]
	v_max_f32_e32 v100, v81, v81
	v_max_f32_e32 v101, v80, v80
	v_max_f32_e32 v100, v101, v100
	v_max3_f32 v100, v100, v82, v83
	v_max3_f32 v100, v100, v84, v85
	v_max3_f32 v100, v100, v86, v87
	v_max3_f32 v100, v100, v88, v89
	v_max3_f32 v100, v100, v90, v91
	v_max3_f32 v100, v100, v92, v93
	v_mfma_f32_32x32x16_bf16 v[16:31], v[104:107], v[120:123], v[16:31]
	v_max3_f32 v100, v100, v94, v95
	v_max3_f32 v100, v100, v64, v65
	v_max3_f32 v100, v100, v66, v67
	v_max3_f32 v100, v100, v68, v69
	v_max3_f32 v100, v100, v70, v71
	v_max3_f32 v100, v100, v72, v73
	v_max3_f32 v100, v100, v74, v75
	v_max3_f32 v100, v100, v76, v77
	v_mfma_f32_32x32x16_bf16 v[16:31], v[108:111], v[124:127], v[16:31]
	v_max3_f32 v100, v100, v78, v79
	v_mov_b32_e32 v101, v100
	s_nop 1
	v_permlane32_swap_b32_e32 v100, v101
	v_max_f32_e32 v101, v101, v101
	v_max_f32_e32 v100, v100, v100
	v_max_f32_e32 v100, v100, v101
	v_sub_f32_e32 v101, v100, v170
	v_cmp_ge_f32_e32 vcc, s92, v101
	v_max_f32_e32 v101, v170, v170
	v_max_f32_e32 v101, v101, v100
	v_mfma_f32_32x32x16_bf16 v[16:31], v[112:115], v[128:131], v[16:31]
	v_sub_f32_e32 v100, v170, v101
	v_mul_f32_e32 v100, 0x3e0293ee, v100
	v_exp_f32_e32 v100, v100
	s_cmp_eq_u64 vcc, exec
	s_cselect_b64 s[42:43], -1, 0
	v_cndmask_b32_e64 v100, v100, 1.0, s[42:43]
	v_cmp_gt_f32_e32 vcc, 1.0, v100
	s_barrier
	s_cbranch_vccz .LBB0_542
	s_and_saveexec_b64 s[6:7], s[40:41]
	ds_write_b32 v184, v100 offset:128
	s_or_b64 exec, exec, s[6:7]
	s_waitcnt lgkmcnt(0)
	ds_read_b128 v[102:105], v182 offset:224
	ds_read_b128 v[106:109], v182 offset:192
	ds_read_b128 v[110:113], v182 offset:160
	ds_read_b128 v[114:117], v182 offset:128
	s_waitcnt lgkmcnt(3)
	v_pk_mul_f32 v[14:15], v[14:15], v[104:105]
	s_waitcnt lgkmcnt(2)
	v_pk_mul_f32 v[10:11], v[10:11], v[108:109]
	s_waitcnt lgkmcnt(1)
	v_pk_mul_f32 v[6:7], v[6:7], v[112:113]
	s_waitcnt lgkmcnt(0)
	v_pk_mul_f32 v[2:3], v[2:3], v[116:117]
	v_pk_mul_f32 v[12:13], v[12:13], v[102:103]
	v_pk_mul_f32 v[8:9], v[8:9], v[106:107]
	v_pk_mul_f32 v[4:5], v[4:5], v[110:111]
	v_pk_mul_f32 v[0:1], v[0:1], v[114:115]
	v_pk_mul_f32 v[62:63], v[62:63], v[104:105]
	v_pk_mul_f32 v[58:59], v[58:59], v[108:109]
	v_pk_mul_f32 v[54:55], v[54:55], v[112:113]
	v_pk_mul_f32 v[50:51], v[50:51], v[116:117]
	v_pk_mul_f32 v[60:61], v[60:61], v[102:103]
	v_pk_mul_f32 v[56:57], v[56:57], v[106:107]
	v_pk_mul_f32 v[52:53], v[52:53], v[110:111]
	v_pk_mul_f32 v[48:49], v[48:49], v[114:115]
	v_pk_mul_f32 v[46:47], v[46:47], v[104:105]
	v_pk_mul_f32 v[42:43], v[42:43], v[108:109]
	v_pk_mul_f32 v[38:39], v[38:39], v[112:113]
	v_pk_mul_f32 v[34:35], v[34:35], v[116:117]
	v_pk_mul_f32 v[44:45], v[44:45], v[102:103]
	v_pk_mul_f32 v[40:41], v[40:41], v[106:107]
	v_pk_mul_f32 v[36:37], v[36:37], v[110:111]
	v_pk_mul_f32 v[32:33], v[32:33], v[114:115]
	v_pk_mul_f32 v[30:31], v[30:31], v[104:105]
	v_pk_mul_f32 v[26:27], v[26:27], v[108:109]
	v_pk_mul_f32 v[22:23], v[22:23], v[112:113]
	v_pk_mul_f32 v[18:19], v[18:19], v[116:117]
	v_pk_mul_f32 v[28:29], v[28:29], v[102:103]
	v_pk_mul_f32 v[24:25], v[24:25], v[106:107]
	v_pk_mul_f32 v[20:21], v[20:21], v[110:111]
	v_pk_mul_f32 v[16:17], v[16:17], v[114:115]
